# P1 rmsnorm loop: norm_g hoisted, all 24 row loads in flight; P4 epilogue residual loads double-buffered
# speedup vs baseline: 1.0136x; 1.0028x over previous
; __device__ __forceinline__ unsigned cvtpk(float lo, float hi) { unsigned r; asm volatile("v_cvt_pk_bf16_f32 %0, %1, %2" : "=v"(r) : "v"(lo), "v"(hi)); return r; }
; #define TIDS() int tid = threadIdx.x; asm volatile("" : "+v"(tid)); const int lane = tid & 63, wid = __builtin_amdgcn_readfirstlane(tid >> 6); (void)lane; (void)wid;
; __global__ void __launch_bounds__(512, 2) fwd_megakernel(Params p) {
;     ...
;     { WSPTRS(); TIDS();
;         const int gw = bid * 8 + wid, NGW = G * 8;
;         for (int R = gw; R < NTOK + NCTX; R += NGW) {
;             const float* src = R < NTOK ? p.x + (size_t)R * DM : p.ctx + (size_t)(R - NTOK) * DM;
;             const float* mr = mod + (R < NTOK ? (R >> 13) : 4) * 6144;
;             f32x4 v[8]; float ss = 0.f;
; #pragma unroll
;             for (int j = 0; j < 8; ++j) { v[j] = __builtin_nontemporal_load((const f32x4*)(src + j * 256 + lane * 4)); ss += (v[j].x * v[j].x + v[j].y * v[j].y) + (v[j].z * v[j].z + v[j].w * v[j].w); }
;             const float rstd = rsqrtf(wave_sum(ss) * (1.f / DM) + 1e-6f);
;             bf16_t* orow = HX + (size_t)R * DM;
; #pragma unroll
;             for (int j = 0; j < 8; ++j) { const int k = j * 256 + lane * 4;
;                 const f32x4 g4 = *(const f32x4*)(p.norm_g + k), sh = *(const f32x4*)(mr + k), sc4 = *(const f32x4*)(mr + 2048 + k);
;                 const f32x4 y = v[j] * rstd * g4 * (sc4 + 1.f) + sh;
;                 uint2 w; w.x = cvtpk(y.x, y.y); w.y = cvtpk(y.z, y.w); *(uint2*)(orow + k) = w; }
.LBB0_57:
	s_or_b64 exec, exec, s[6:7]
	s_mov_b64 s[6:7], 0
	v_mov_b32_e32 v0, v200
	s_barrier
	v_mbcnt_lo_u32_b32 v201, -1, 0
	v_readfirstlane_b32 s0, v0
	s_ashr_i32 s0, s0, 6
	s_add_i32 s1, s0, s2
	s_cmp_gt_i32 s1, 0x83ff
	s_cbranch_scc1 .LBB0_62
	v_mbcnt_hi_u32_b32 v1, -1, v201
	v_and_b32_e32 v2, 64, v1
	v_add_u32_e32 v2, 64, v2
	v_xor_b32_e32 v3, 1, v1
	v_cmp_lt_i32_e32 vcc, v3, v2
	v_lshlrev_b32_e32 v0, 2, v0
	v_and_b32_e32 v0, 0xfc, v0
	v_cndmask_b32_e32 v3, v1, v3, vcc
	v_lshlrev_b32_e32 v42, 2, v3
	v_xor_b32_e32 v3, 2, v1
	v_cmp_lt_i32_e32 vcc, v3, v2
	v_mov_b32_e32 v29, 0
	v_lshlrev_b32_e32 v28, 2, v0
	v_cndmask_b32_e32 v3, v1, v3, vcc
	v_lshlrev_b32_e32 v43, 2, v3
	v_xor_b32_e32 v3, 4, v1
	v_cmp_lt_i32_e32 vcc, v3, v2
	v_or_b32_e32 v8, 0x400, v0
	v_lshl_add_u64 v[30:31], s[44:45], 0, v[28:29]
	v_cndmask_b32_e32 v3, v1, v3, vcc
	v_lshlrev_b32_e32 v28, 2, v8
	v_or_b32_e32 v10, 0x500, v0
	v_lshlrev_b32_e32 v44, 2, v3
	v_xor_b32_e32 v3, 8, v1
	v_lshl_add_u64 v[32:33], s[44:45], 0, v[28:29]
	v_lshlrev_b32_e32 v28, 2, v10
	v_or_b32_e32 v12, 0x600, v0
	v_cmp_lt_i32_e32 vcc, v3, v2
	v_lshl_add_u64 v[34:35], s[44:45], 0, v[28:29]
	v_lshlrev_b32_e32 v28, 2, v12
	v_or_b32_e32 v14, 0x700, v0
	s_add_u32 s6, s86, s6
	v_cndmask_b32_e32 v3, v1, v3, vcc
	v_lshl_add_u64 v[36:37], s[44:45], 0, v[28:29]
	v_lshlrev_b32_e32 v28, 2, v14
	s_addc_u32 s7, s87, s7
	v_lshlrev_b32_e32 v45, 2, v3
	v_xor_b32_e32 v3, 16, v1
	v_lshl_add_u64 v[38:39], s[44:45], 0, v[28:29]
	v_lshlrev_b32_e32 v28, 1, v0
	v_cmp_lt_i32_e32 vcc, v3, v2
	v_lshl_add_u64 v[16:17], s[6:7], 0, v[28:29]
	s_mov_b64 s[10:11], 0x3000000
	s_ashr_i32 s1, s0, 31
	s_ashr_i32 s5, s2, 31
	v_cndmask_b32_e32 v3, v1, v3, vcc
	v_lshl_add_u64 v[40:41], v[16:17], 0, s[10:11]
	s_add_u32 s10, s0, s2
	v_lshlrev_b32_e32 v46, 2, v3
	v_xor_b32_e32 v3, 32, v1
	s_addc_u32 s11, s1, s5
	v_cmp_lt_i32_e32 vcc, v3, v2
	s_ashr_i32 s5, s4, 31
	s_lshl_b64 s[0:1], s[10:11], 13
	v_cndmask_b32_e32 v1, v1, v3, vcc
	v_or_b32_e32 v2, 0x100, v0
	v_or_b32_e32 v4, 0x200, v0
	v_or_b32_e32 v6, 0x300, v0
	s_add_u32 s12, s36, s0
	s_mov_b32 s9, 0
	v_lshlrev_b32_e32 v47, 2, v1
	s_addc_u32 s13, s37, s1
	s_lshl_b64 s[14:15], s[4:5], 13
	v_lshlrev_b32_e32 v28, 2, v0
	s_movk_i32 s0, 0x1000
	v_mov_b32_e32 v48, 0x358637bd
	s_mov_b32 s1, 0x800000
	v_lshlrev_b32_e32 v49, 2, v2
	v_lshlrev_b32_e32 v50, 2, v4
	v_lshlrev_b32_e32 v51, 2, v6
	v_lshlrev_b32_e32 v52, 2, v8
	v_lshlrev_b32_e32 v53, 2, v10
	v_lshlrev_b32_e32 v54, 2, v12
	v_lshlrev_b32_e32 v55, 2, v14
	global_load_dwordx4 v[96:99], v[30:31], off
	global_load_dwordx4 v[100:103], v[30:31], off offset:1024
	global_load_dwordx4 v[104:107], v[30:31], off offset:2048
	global_load_dwordx4 v[108:111], v[30:31], off offset:3072
	global_load_dwordx4 v[112:115], v[32:33], off
	global_load_dwordx4 v[116:119], v[34:35], off
	global_load_dwordx4 v[120:123], v[36:37], off
	global_load_dwordx4 v[124:127], v[38:39], off

; __global__ void __launch_bounds__(512, 2) fwd_megakernel(Params p) {
;     ...
;         for (int R = gw; R < NTOK + NCTX; R += NGW) {
;             const float* src = R < NTOK ? p.x + (size_t)R * DM : p.ctx + (size_t)(R - NTOK) * DM;
;             const float* mr = mod + (R < NTOK ? (R >> 13) : 4) * 6144;
;             f32x4 v[8]; float ss = 0.f;
; #pragma unroll
;             for (int j = 0; j < 8; ++j) { v[j] = __builtin_nontemporal_load((const f32x4*)(src + j * 256 + lane * 4)); ss += (v[j].x * v[j].x + v[j].y * v[j].y) + (v[j].z * v[j].z + v[j].w * v[j].w); }
;     ...
;                 const f32x4 g4 = *(const f32x4*)(p.norm_g + k), sh = *(const f32x4*)(mr + k), sc4 = *(const f32x4*)(mr + 2048 + k);
.Lp1_x:
	global_load_dwordx4 v[56:59], v28, s[16:17] nt
	global_load_dwordx4 v[24:27], v28, s[16:17] offset:1024 nt
	global_load_dwordx4 v[20:23], v28, s[16:17] offset:2048 nt
	global_load_dwordx4 v[16:19], v28, s[16:17] offset:3072 nt
	global_load_dwordx4 v[12:15], v52, s[16:17] nt
	global_load_dwordx4 v[8:11], v52, s[16:17] offset:1024 nt
	global_load_dwordx4 v[4:7], v52, s[16:17] offset:2048 nt
	global_load_dwordx4 v[0:3], v52, s[16:17] offset:3072 nt
	s_min_i32 s2, s10, 0x8000
	s_ashr_i32 s2, s2, 13
	s_mul_i32 s16, s2, 0x1800
	s_ashr_i32 s17, s16, 31
	s_lshl_b64 s[16:17], s[16:17], 2
	s_add_u32 s16, s6, s16
	s_addc_u32 s17, s7, s17
	s_lshl_b64 s[20:21], s[18:19], 12
	s_add_u32 s18, s16, 0x2000
	s_addc_u32 s19, s17, 0
	global_load_dwordx4 v[128:131], v28, s[16:17]
	global_load_dwordx4 v[132:135], v28, s[16:17] offset:1024
	global_load_dwordx4 v[136:139], v28, s[16:17] offset:2048
	global_load_dwordx4 v[140:143], v28, s[16:17] offset:3072
	global_load_dwordx4 v[144:147], v52, s[16:17]
	global_load_dwordx4 v[148:151], v52, s[16:17] offset:1024
	global_load_dwordx4 v[152:155], v52, s[16:17] offset:2048
	global_load_dwordx4 v[156:159], v52, s[16:17] offset:3072
	global_load_dwordx4 v[160:163], v28, s[18:19]
	global_load_dwordx4 v[164:167], v28, s[18:19] offset:1024
	global_load_dwordx4 v[168:171], v28, s[18:19] offset:2048
	global_load_dwordx4 v[172:175], v28, s[18:19] offset:3072
	global_load_dwordx4 v[176:179], v52, s[18:19]
	global_load_dwordx4 v[180:183], v52, s[18:19] offset:1024
	global_load_dwordx4 v[184:187], v52, s[18:19] offset:2048
	global_load_dwordx4 v[188:191], v52, s[18:19] offset:3072
	s_add_u32 s10, s10, s4
	s_addc_u32 s11, s11, s5
	s_add_u32 s12, s12, s14
	s_addc_u32 s13, s13, s15
; __device__ __forceinline__ unsigned cvtpk(float lo, float hi) { unsigned r; asm volatile("v_cvt_pk_bf16_f32 %0, %1, %2" : "=v"(r) : "v"(lo), "v"(hi)); return r; }
; __global__ void __launch_bounds__(512, 2) fwd_megakernel(Params p) {
;     ...
;             f32x4 v[8]; float ss = 0.f;
; #pragma unroll
;             for (int j = 0; j < 8; ++j) { v[j] = __builtin_nontemporal_load((const f32x4*)(src + j * 256 + lane * 4)); ss += (v[j].x * v[j].x + v[j].y * v[j].y) + (v[j].z * v[j].z + v[j].w * v[j].w); }
;             const float rstd = rsqrtf(wave_sum(ss) * (1.f / DM) + 1e-6f);
;             bf16_t* orow = HX + (size_t)R * DM;
; #pragma unroll
;             for (int j = 0; j < 8; ++j) { const int k = j * 256 + lane * 4;
;                 const f32x4 g4 = *(const f32x4*)(p.norm_g + k), sh = *(const f32x4*)(mr + k), sc4 = *(const f32x4*)(mr + 2048 + k);
;                 const f32x4 y = v[j] * rstd * g4 * (sc4 + 1.f) + sh;
;                 uint2 w; w.x = cvtpk(y.x, y.y); w.y = cvtpk(y.z, y.w); *(uint2*)(orow + k) = w; }
.Lp1_loop:
	s_waitcnt vmcnt(16)
	v_mul_f32_e32 v81, v57, v57
	v_mul_f32_e32 v82, v59, v59
	v_fmac_f32_e32 v81, v56, v56
	v_fmac_f32_e32 v82, v58, v58
	v_add_f32_e32 v80, v81, v82
	v_mul_f32_e32 v81, v25, v25
	v_mul_f32_e32 v82, v27, v27
	v_fmac_f32_e32 v81, v24, v24
	v_fmac_f32_e32 v82, v26, v26
	v_add_f32_e32 v81, v81, v82
	v_add_f32_e32 v80, v80, v81
	v_mul_f32_e32 v81, v21, v21
	v_mul_f32_e32 v82, v23, v23
	v_fmac_f32_e32 v81, v20, v20
	v_fmac_f32_e32 v82, v22, v22
	v_add_f32_e32 v81, v81, v82
	v_add_f32_e32 v80, v80, v81
	v_mul_f32_e32 v81, v17, v17
	v_mul_f32_e32 v82, v19, v19
	v_fmac_f32_e32 v81, v16, v16
	v_fmac_f32_e32 v82, v18, v18
	v_add_f32_e32 v81, v81, v82
	v_add_f32_e32 v80, v80, v81
	v_mul_f32_e32 v81, v13, v13
	v_mul_f32_e32 v82, v15, v15
	v_fmac_f32_e32 v81, v12, v12
	v_fmac_f32_e32 v82, v14, v14
	v_add_f32_e32 v81, v81, v82
	v_add_f32_e32 v80, v80, v81
	v_mul_f32_e32 v81, v9, v9
	v_mul_f32_e32 v82, v11, v11
	v_fmac_f32_e32 v81, v8, v8
	v_fmac_f32_e32 v82, v10, v10
	v_add_f32_e32 v81, v81, v82
	v_add_f32_e32 v80, v80, v81
	v_mul_f32_e32 v81, v5, v5
	v_mul_f32_e32 v82, v7, v7
	v_fmac_f32_e32 v81, v4, v4
	v_fmac_f32_e32 v82, v6, v6
	v_add_f32_e32 v81, v81, v82
	v_add_f32_e32 v80, v80, v81
	v_mul_f32_e32 v81, v1, v1
	v_mul_f32_e32 v82, v3, v3
	v_fmac_f32_e32 v81, v0, v0
	v_fmac_f32_e32 v82, v2, v2
	v_add_f32_e32 v81, v81, v82
	v_add_f32_e32 v80, v80, v81
	ds_bpermute_b32 v83, v42, v80
	s_waitcnt lgkmcnt(0)
	v_add_f32_e32 v80, v80, v83
	ds_bpermute_b32 v83, v43, v80
	s_waitcnt lgkmcnt(0)
	v_add_f32_e32 v80, v80, v83
	ds_bpermute_b32 v83, v44, v80
	s_waitcnt lgkmcnt(0)
	v_add_f32_e32 v80, v80, v83
	ds_bpermute_b32 v83, v45, v80
	s_waitcnt lgkmcnt(0)
	v_add_f32_e32 v80, v80, v83
	ds_bpermute_b32 v83, v46, v80
	s_waitcnt lgkmcnt(0)
	v_add_f32_e32 v80, v80, v83
	ds_bpermute_b32 v83, v47, v80
	s_waitcnt lgkmcnt(0)
	v_add_f32_e32 v80, v80, v83
	v_fmamk_f32 v80, v80, 0x3a000000, v48
	v_mul_f32_e32 v81, 0x4b800000, v80
	v_cmp_gt_f32_e32 vcc, s1, v80
	s_nop 1
	v_cndmask_b32_e32 v80, v80, v81, vcc
	v_rsq_f32_e32 v84, v80
	v_lshl_add_u64 v[92:93], v[40:41], 0, s[20:21]
	s_nop 0
	v_mul_f32_e32 v85, 0x45800000, v84
	s_nop 0
	v_cndmask_b32_e32 v84, v84, v85, vcc
	s_waitcnt vmcnt(0)
	v_pk_mul_f32 v[56:57], v[84:85], v[56:57] op_sel_hi:[0,1]
	v_pk_add_f32 v[160:161], v[160:161], 1.0 op_sel_hi:[1,0]
	v_pk_mul_f32 v[56:57], v[56:57], v[96:97]
	v_pk_fma_f32 v[56:57], v[56:57], v[160:161], v[128:129]
	v_pk_mul_f32 v[58:59], v[84:85], v[58:59] op_sel_hi:[0,1]
	v_pk_add_f32 v[162:163], v[162:163], 1.0 op_sel_hi:[1,0]
	v_pk_mul_f32 v[58:59], v[58:59], v[98:99]
	v_pk_fma_f32 v[58:59], v[58:59], v[162:163], v[130:131]
	v_cvt_pk_bf16_f32 v64, v56, v57
	v_cvt_pk_bf16_f32 v65, v58, v59
	v_pk_mul_f32 v[24:25], v[84:85], v[24:25] op_sel_hi:[0,1]
	v_pk_add_f32 v[164:165], v[164:165], 1.0 op_sel_hi:[1,0]
	v_pk_mul_f32 v[24:25], v[24:25], v[100:101]
	v_pk_fma_f32 v[24:25], v[24:25], v[164:165], v[132:133]
	v_pk_mul_f32 v[26:27], v[84:85], v[26:27] op_sel_hi:[0,1]
	v_pk_add_f32 v[166:167], v[166:167], 1.0 op_sel_hi:[1,0]
	v_pk_mul_f32 v[26:27], v[26:27], v[102:103]
	v_pk_fma_f32 v[26:27], v[26:27], v[166:167], v[134:135]
	v_cvt_pk_bf16_f32 v66, v24, v25
	v_cvt_pk_bf16_f32 v67, v26, v27
	v_pk_mul_f32 v[20:21], v[84:85], v[20:21] op_sel_hi:[0,1]
	v_pk_add_f32 v[168:169], v[168:169], 1.0 op_sel_hi:[1,0]
	v_pk_mul_f32 v[20:21], v[20:21], v[104:105]
	v_pk_fma_f32 v[20:21], v[20:21], v[168:169], v[136:137]
	v_pk_mul_f32 v[22:23], v[84:85], v[22:23] op_sel_hi:[0,1]
	v_pk_add_f32 v[170:171], v[170:171], 1.0 op_sel_hi:[1,0]
	v_pk_mul_f32 v[22:23], v[22:23], v[106:107]
	v_pk_fma_f32 v[22:23], v[22:23], v[170:171], v[138:139]
	v_cvt_pk_bf16_f32 v68, v20, v21
	v_cvt_pk_bf16_f32 v69, v22, v23
	v_pk_mul_f32 v[16:17], v[84:85], v[16:17] op_sel_hi:[0,1]
	v_pk_add_f32 v[172:173], v[172:173], 1.0 op_sel_hi:[1,0]
	v_pk_mul_f32 v[16:17], v[16:17], v[108:109]
	v_pk_fma_f32 v[16:17], v[16:17], v[172:173], v[140:141]
	v_pk_mul_f32 v[18:19], v[84:85], v[18:19] op_sel_hi:[0,1]
	v_pk_add_f32 v[174:175], v[174:175], 1.0 op_sel_hi:[1,0]
	v_pk_mul_f32 v[18:19], v[18:19], v[110:111]
	v_pk_fma_f32 v[18:19], v[18:19], v[174:175], v[142:143]
	v_cvt_pk_bf16_f32 v70, v16, v17
	v_cvt_pk_bf16_f32 v71, v18, v19
	v_pk_mul_f32 v[12:13], v[84:85], v[12:13] op_sel_hi:[0,1]
	v_pk_add_f32 v[176:177], v[176:177], 1.0 op_sel_hi:[1,0]
	v_pk_mul_f32 v[12:13], v[12:13], v[112:113]
	v_pk_fma_f32 v[12:13], v[12:13], v[176:177], v[144:145]
	v_pk_mul_f32 v[14:15], v[84:85], v[14:15] op_sel_hi:[0,1]
	v_pk_add_f32 v[178:179], v[178:179], 1.0 op_sel_hi:[1,0]
	v_pk_mul_f32 v[14:15], v[14:15], v[114:115]
	v_pk_fma_f32 v[14:15], v[14:15], v[178:179], v[146:147]
	v_cvt_pk_bf16_f32 v72, v12, v13
	v_cvt_pk_bf16_f32 v73, v14, v15
	v_pk_mul_f32 v[8:9], v[84:85], v[8:9] op_sel_hi:[0,1]
	v_pk_add_f32 v[180:181], v[180:181], 1.0 op_sel_hi:[1,0]
	v_pk_mul_f32 v[8:9], v[8:9], v[116:117]
	v_pk_fma_f32 v[8:9], v[8:9], v[180:181], v[148:149]
	v_pk_mul_f32 v[10:11], v[84:85], v[10:11] op_sel_hi:[0,1]
	v_pk_add_f32 v[182:183], v[182:183], 1.0 op_sel_hi:[1,0]
	v_pk_mul_f32 v[10:11], v[10:11], v[118:119]
	v_pk_fma_f32 v[10:11], v[10:11], v[182:183], v[150:151]
	v_cvt_pk_bf16_f32 v74, v8, v9
	v_cvt_pk_bf16_f32 v75, v10, v11
	v_pk_mul_f32 v[4:5], v[84:85], v[4:5] op_sel_hi:[0,1]
	v_pk_add_f32 v[184:185], v[184:185], 1.0 op_sel_hi:[1,0]
	v_pk_mul_f32 v[4:5], v[4:5], v[120:121]
	v_pk_fma_f32 v[4:5], v[4:5], v[184:185], v[152:153]
	v_pk_mul_f32 v[6:7], v[84:85], v[6:7] op_sel_hi:[0,1]
	v_pk_add_f32 v[186:187], v[186:187], 1.0 op_sel_hi:[1,0]
	v_pk_mul_f32 v[6:7], v[6:7], v[122:123]
	v_pk_fma_f32 v[6:7], v[6:7], v[186:187], v[154:155]
	v_cvt_pk_bf16_f32 v76, v4, v5
	v_cvt_pk_bf16_f32 v77, v6, v7
	v_pk_mul_f32 v[0:1], v[84:85], v[0:1] op_sel_hi:[0,1]
	v_pk_add_f32 v[188:189], v[188:189], 1.0 op_sel_hi:[1,0]
	v_pk_mul_f32 v[0:1], v[0:1], v[124:125]
	v_pk_fma_f32 v[0:1], v[0:1], v[188:189], v[156:157]
	v_pk_mul_f32 v[2:3], v[84:85], v[2:3] op_sel_hi:[0,1]
	v_pk_add_f32 v[190:191], v[190:191], 1.0 op_sel_hi:[1,0]
	v_pk_mul_f32 v[2:3], v[2:3], v[126:127]
	v_pk_fma_f32 v[2:3], v[2:3], v[190:191], v[158:159]
	v_cvt_pk_bf16_f32 v78, v0, v1
	v_cvt_pk_bf16_f32 v79, v2, v3
	global_store_dwordx2 v[92:93], v[64:65], off
	global_store_dwordx2 v[92:93], v[66:67], off offset:512
	global_store_dwordx2 v[92:93], v[68:69], off offset:1024
	global_store_dwordx2 v[92:93], v[70:71], off offset:1536
	global_store_dwordx2 v[92:93], v[72:73], off offset:2048
	global_store_dwordx2 v[92:93], v[74:75], off offset:2560
	global_store_dwordx2 v[92:93], v[76:77], off offset:3072
	global_store_dwordx2 v[92:93], v[78:79], off offset:3584
	s_cmp_gt_i32 s10, 0x83ff
	s_cbranch_scc0 .Lp1_issue

;     __device__ __forceinline__ void operator()(f32x4 (&acc)[2][2][4][2], const pg8::Unit& u, int wr, int wc, int fr, int fq) const {
;         const int row0 = u.pm * 256 + wr * 64 + fr, b = u.pm >> 5, col0 = u.pn * 256 + wc * 32 + 8 * fq;
;         int tid = threadIdx.x; asm volatile("" : "+v"(tid));
;         f32x4 gv[2][2];
; #pragma unroll
;         for (int bj = 0; bj < 2; ++bj)
; #pragma unroll
;             for (int n = 0; n < 2; ++n) gv[bj][n] = *(const f32x4*)(mod + b * 6144 + 4096 + col0 + bj * 128 + 4 * n);
; #pragma unroll
;         for (int ai = 0; ai < 2; ++ai)
; #pragma unroll
;             for (int m = 0; m < 4; ++m) {
;                 const size_t ro = (size_t)(row0 + ai * 128 + m * 16) * DM + col0;
;                 float s = 0.f;
; #pragma unroll
;                 for (int bj = 0; bj < 2; ++bj) {
;                     const f32x4 x0 = __builtin_nontemporal_load((const f32x4*)(x + ro + bj * 128)), x1 = __builtin_nontemporal_load((const f32x4*)(x + ro + bj * 128 + 4));
;                     const f32x4 h0 = x0 + gv[bj][0] * acc[ai][bj][m][0], h1 = x1 + gv[bj][1] * acc[ai][bj][m][1];
;                     acc[ai][bj][m][0] = h0; acc[ai][bj][m][1] = h1;
;                     s += (h0.x * h0.x + h0.y * h0.y) + (h0.z * h0.z + h0.w * h0.w) + (h1.x * h1.x + h1.y * h1.y) + (h1.z * h1.z + h1.w * h1.w);
;                 }
;                 s += __shfl_xor(s, 16); s += __shfl_xor(s, 32);
;                 if (fq == 0) sc[wc * 256 + ai * 128 + wr * 64 + m * 16 + fr] = s;
.LBB0_326:
	s_lshr_b32 s2, s28, 5
	s_mulk_i32 s2, 0x1800
	s_ashr_i32 s3, s2, 31
	s_lshl_b64 s[2:3], s[2:3], 2
	s_add_u32 s2, s33, s2
	s_addc_u32 s3, s40, s3
	v_lshl_add_u32 v178, s28, 8, v186
	v_lshl_add_u64 v[128:129], s[2:3], 0, v[152:153]
	v_ashrrev_i32_e32 v179, 31, v178
	v_add_co_u32_e32 v138, vcc, s48, v128
	v_lshlrev_b64 v[166:167], 13, v[178:179]
	v_mov_b32_e32 v164, v200
	v_lshl_add_u64 v[136:137], v[128:129], 0, s[18:19]
	v_addc_co_u32_e32 v139, vcc, 0, v129, vcc
	v_lshl_add_u64 v[176:177], v[154:155], 0, v[166:167]
	global_load_dwordx4 v[132:135], v[136:137], off offset:16
	global_load_dwordx4 v[128:131], v[136:137], off offset:512
	global_load_dwordx4 v[140:143], v[138:139], off
	s_nop 0
	global_load_dwordx4 v[136:139], v[136:137], off offset:528
	v_lshl_add_u32 v234, s28, 8, v186
	v_mov_b32_e32 v235, 0
	v_lshlrev_b64 v[234:235], 13, v[234:235]
	v_lshl_add_u64 v[236:237], v[154:155], 0, v[234:235]
	global_load_dwordx4 v[222:225], v[236:237], off nt
	global_load_dwordx4 v[226:229], v[236:237], off offset:16 nt
	global_load_dwordx4 v[230:233], v[236:237], off offset:512 nt
	s_nop 0
	global_load_dwordx4 v[234:237], v[236:237], off offset:528 nt
	v_lshl_add_u32 v250, s28, 8, v186
	v_or_b32_e32 v250, 0x10, v250
	v_mov_b32_e32 v251, 0
	v_lshlrev_b64 v[250:251], 13, v[250:251]
	v_lshl_add_u64 v[252:253], v[154:155], 0, v[250:251]
	global_load_dwordx4 v[238:241], v[252:253], off nt
	global_load_dwordx4 v[242:245], v[252:253], off offset:16 nt
	global_load_dwordx4 v[246:249], v[252:253], off offset:512 nt
	s_nop 0
	global_load_dwordx4 v[250:253], v[252:253], off offset:528 nt
	v_and_b32_e32 v176, 64, v195
	v_xor_b32_e32 v165, 16, v195
	v_add_u32_e32 v176, 64, v176
	v_cmp_lt_i32_e32 vcc, v165, v176
	s_waitcnt vmcnt(4)
	v_pk_fma_f32 v[126:127], v[126:127], v[134:135], v[228:229]
	v_pk_fma_f32 v[124:125], v[124:125], v[132:133], v[226:227]
	v_pk_fma_f32 v[118:119], v[118:119], v[130:131], v[232:233]
	v_pk_fma_f32 v[116:117], v[116:117], v[128:129], v[230:231]
	v_pk_fma_f32 v[122:123], v[122:123], v[142:143], v[224:225]
	v_pk_fma_f32 v[120:121], v[120:121], v[140:141], v[222:223]
	v_pk_fma_f32 v[112:113], v[112:113], v[136:137], v[234:235]
	v_mul_f32_e32 v170, v117, v117
	v_mul_f32_e32 v171, v119, v119
	v_mul_f32_e32 v172, v121, v121
	v_mul_f32_e32 v173, v123, v123
	v_mul_f32_e32 v168, v125, v125
	v_pk_fma_f32 v[114:115], v[114:115], v[138:139], v[236:237]
	v_fmac_f32_e32 v170, v116, v116
	v_fmac_f32_e32 v171, v118, v118
	v_mul_f32_e32 v174, v113, v113
	v_fmac_f32_e32 v172, v120, v120
	v_fmac_f32_e32 v173, v122, v122
	v_mul_f32_e32 v169, v127, v127
	v_fmac_f32_e32 v168, v124, v124
	v_mul_f32_e32 v175, v115, v115
	v_add_f32_e32 v170, v170, v171
	v_fmac_f32_e32 v174, v112, v112
	v_add_f32_e32 v171, v172, v173
	v_fmac_f32_e32 v169, v126, v126
	v_fmac_f32_e32 v175, v114, v114
	v_add_f32_e32 v170, v170, v174
	v_add_f32_e32 v168, v171, v168
	v_cndmask_b32_e32 v165, v195, v165, vcc
	v_add_f32_e32 v168, v169, v168
	v_add_f32_e32 v169, v175, v170
	v_lshlrev_b32_e32 v165, 2, v165
	v_add_f32_e32 v168, v168, v169
	ds_bpermute_b32 v169, v165, v168
	v_xor_b32_e32 v170, 32, v195
	v_cmp_lt_i32_e32 vcc, v170, v176
	s_waitcnt lgkmcnt(0)
	v_add_f32_e32 v168, v168, v169
	v_cndmask_b32_e32 v170, v195, v170, vcc
	v_lshlrev_b32_e32 v197, 2, v170
	ds_bpermute_b32 v169, v197, v168
	s_and_saveexec_b64 s[2:3], s[0:1]
	s_cbranch_execz .LBB0_328
	s_waitcnt lgkmcnt(0)
	v_add_f32_e32 v168, v168, v169
	ds_write_b32 v188, v168
.LBB0_328:
	s_or_b64 exec, exec, s[2:3]
	v_or_b32_e32 v168, 16, v178
	s_waitcnt lgkmcnt(0)
	v_ashrrev_i32_e32 v169, 31, v168
	v_lshlrev_b64 v[168:169], 13, v[168:169]
	v_lshl_add_u64 v[184:185], v[154:155], 0, v[168:169]
	v_lshl_add_u32 v234, s28, 8, v186
	v_or_b32_e32 v234, 0x20, v234
	v_mov_b32_e32 v235, 0
	v_lshlrev_b64 v[234:235], 13, v[234:235]
	v_lshl_add_u64 v[236:237], v[154:155], 0, v[234:235]
	global_load_dwordx4 v[222:225], v[236:237], off nt
	global_load_dwordx4 v[226:229], v[236:237], off offset:16 nt
	global_load_dwordx4 v[230:233], v[236:237], off offset:512 nt
	s_nop 0
	global_load_dwordx4 v[234:237], v[236:237], off offset:528 nt
	s_waitcnt vmcnt(7)
	v_pk_fma_f32 v[110:111], v[110:111], v[142:143], v[240:241]
	v_pk_fma_f32 v[108:109], v[108:109], v[140:141], v[238:239]
	s_waitcnt vmcnt(5)
	v_pk_fma_f32 v[102:103], v[102:103], v[130:131], v[248:249]
	v_pk_fma_f32 v[100:101], v[100:101], v[128:129], v[246:247]
	v_pk_fma_f32 v[104:105], v[104:105], v[132:133], v[242:243]
	s_waitcnt vmcnt(4)
	v_pk_fma_f32 v[96:97], v[96:97], v[136:137], v[250:251]
	v_mul_f32_e32 v170, v109, v109
	v_mul_f32_e32 v171, v111, v111
	v_mul_f32_e32 v174, v101, v101
	v_mul_f32_e32 v175, v103, v103
	v_pk_fma_f32 v[106:107], v[106:107], v[134:135], v[244:245]
	v_pk_fma_f32 v[98:99], v[98:99], v[138:139], v[252:253]
	v_mul_f32_e32 v172, v105, v105
	v_mul_f32_e32 v176, v97, v97
	v_fmac_f32_e32 v170, v108, v108
	v_fmac_f32_e32 v171, v110, v110
	v_fmac_f32_e32 v174, v100, v100
	v_fmac_f32_e32 v175, v102, v102
	v_mul_f32_e32 v173, v107, v107
	v_mul_f32_e32 v177, v99, v99
	v_fmac_f32_e32 v172, v104, v104
	v_fmac_f32_e32 v176, v96, v96
	v_add_f32_e32 v170, v170, v171
	v_add_f32_e32 v171, v174, v175
	v_fmac_f32_e32 v173, v106, v106
	v_fmac_f32_e32 v177, v98, v98
	v_add_f32_e32 v170, v170, v172
	v_add_f32_e32 v171, v171, v176
	v_add_f32_e32 v170, v173, v170
	v_add_f32_e32 v171, v177, v171
	v_add_f32_e32 v170, v170, v171
	ds_bpermute_b32 v171, v165, v170
	s_waitcnt lgkmcnt(0)
	v_add_f32_e32 v170, v170, v171
	ds_bpermute_b32 v171, v197, v170
	s_and_saveexec_b64 s[2:3], s[0:1]
	s_cbranch_execz .LBB0_330
	s_waitcnt lgkmcnt(0)
	v_add_f32_e32 v170, v170, v171
	ds_write_b32 v188, v170 offset:64
;     __device__ __forceinline__ void operator()(f32x4 (&acc)[2][2][4][2], const pg8::Unit& u, int wr, int wc, int fr, int fq) const {
;     ...
;         for (int ai = 0; ai < 2; ++ai)
; #pragma unroll
;             for (int m = 0; m < 4; ++m) {
;                 const size_t ro = (size_t)(row0 + ai * 128 + m * 16) * DM + col0;
;                 float s = 0.f;
; #pragma unroll
;                 for (int bj = 0; bj < 2; ++bj) {
;                     const f32x4 x0 = __builtin_nontemporal_load((const f32x4*)(x + ro + bj * 128)), x1 = __builtin_nontemporal_load((const f32x4*)(x + ro + bj * 128 + 4));
;                     const f32x4 h0 = x0 + gv[bj][0] * acc[ai][bj][m][0], h1 = x1 + gv[bj][1] * acc[ai][bj][m][1];
;                     acc[ai][bj][m][0] = h0; acc[ai][bj][m][1] = h1;
;                     s += (h0.x * h0.x + h0.y * h0.y) + (h0.z * h0.z + h0.w * h0.w) + (h1.x * h1.x + h1.y * h1.y) + (h1.z * h1.z + h1.w * h1.w);
;                 }
;                 s += __shfl_xor(s, 16); s += __shfl_xor(s, 32);
;                 if (fq == 0) sc[wc * 256 + ai * 128 + wr * 64 + m * 16 + fr] = s;
.LBB0_330:
	s_or_b64 exec, exec, s[2:3]
	v_or_b32_e32 v170, 32, v178
	s_waitcnt lgkmcnt(0)
	v_ashrrev_i32_e32 v171, 31, v170
	v_lshlrev_b64 v[170:171], 13, v[170:171]
	v_lshl_add_u64 v[176:177], v[154:155], 0, v[170:171]
	v_lshl_add_u32 v250, s28, 8, v186
	v_or_b32_e32 v250, 0x30, v250
	v_mov_b32_e32 v251, 0
	v_lshlrev_b64 v[250:251], 13, v[250:251]
	v_lshl_add_u64 v[252:253], v[154:155], 0, v[250:251]
	global_load_dwordx4 v[238:241], v[252:253], off nt
	global_load_dwordx4 v[242:245], v[252:253], off offset:16 nt
	global_load_dwordx4 v[246:249], v[252:253], off offset:512 nt
	s_nop 0
	global_load_dwordx4 v[250:253], v[252:253], off offset:528 nt
	s_waitcnt vmcnt(7)
	v_pk_fma_f32 v[94:95], v[94:95], v[142:143], v[224:225]
	v_pk_fma_f32 v[92:93], v[92:93], v[140:141], v[222:223]
	s_waitcnt vmcnt(5)
	v_pk_fma_f32 v[86:87], v[86:87], v[130:131], v[232:233]
	v_pk_fma_f32 v[84:85], v[84:85], v[128:129], v[230:231]
	v_pk_fma_f32 v[88:89], v[88:89], v[132:133], v[226:227]
	s_waitcnt vmcnt(4)
	v_pk_fma_f32 v[80:81], v[80:81], v[136:137], v[234:235]
	v_mul_f32_e32 v172, v93, v93
	v_mul_f32_e32 v173, v95, v95
	v_mul_f32_e32 v176, v85, v85
	v_mul_f32_e32 v177, v87, v87
	v_pk_fma_f32 v[90:91], v[90:91], v[134:135], v[228:229]
	v_pk_fma_f32 v[82:83], v[82:83], v[138:139], v[236:237]
	v_mul_f32_e32 v174, v89, v89
	v_mul_f32_e32 v180, v81, v81
	v_fmac_f32_e32 v172, v92, v92
	v_fmac_f32_e32 v173, v94, v94
	v_fmac_f32_e32 v176, v84, v84
	v_fmac_f32_e32 v177, v86, v86
	v_mul_f32_e32 v175, v91, v91
	v_mul_f32_e32 v181, v83, v83
	v_fmac_f32_e32 v174, v88, v88
	v_fmac_f32_e32 v180, v80, v80
	v_add_f32_e32 v172, v172, v173
	v_add_f32_e32 v173, v176, v177
	v_fmac_f32_e32 v175, v90, v90
	v_fmac_f32_e32 v181, v82, v82
	v_add_f32_e32 v172, v172, v174
	v_add_f32_e32 v173, v173, v180
	v_add_f32_e32 v172, v175, v172
	v_add_f32_e32 v173, v181, v173
	v_add_f32_e32 v172, v172, v173
	ds_bpermute_b32 v173, v165, v172
	s_waitcnt lgkmcnt(0)
	v_add_f32_e32 v172, v172, v173
	ds_bpermute_b32 v173, v197, v172
	s_and_saveexec_b64 s[2:3], s[0:1]
	s_cbranch_execz .LBB0_332
	s_waitcnt lgkmcnt(0)
	v_add_f32_e32 v172, v172, v173
	ds_write_b32 v188, v172 offset:128
.LBB0_332:
	s_or_b64 exec, exec, s[2:3]
	v_or_b32_e32 v172, 48, v178
	s_waitcnt lgkmcnt(0)
	v_ashrrev_i32_e32 v173, 31, v172
	v_lshlrev_b64 v[174:175], 13, v[172:173]
	v_lshl_add_u64 v[172:173], v[154:155], 0, v[174:175]
	v_lshl_add_u32 v234, s28, 8, v186
	v_or_b32_e32 v234, 0x80, v234
	v_mov_b32_e32 v235, 0
	v_lshlrev_b64 v[234:235], 13, v[234:235]
	v_lshl_add_u64 v[236:237], v[154:155], 0, v[234:235]
	global_load_dwordx4 v[222:225], v[236:237], off nt
	global_load_dwordx4 v[226:229], v[236:237], off offset:16 nt
	global_load_dwordx4 v[230:233], v[236:237], off offset:512 nt
	s_nop 0
	global_load_dwordx4 v[234:237], v[236:237], off offset:528 nt
	s_waitcnt vmcnt(7)
	v_pk_fma_f32 v[78:79], v[78:79], v[142:143], v[240:241]
	v_pk_fma_f32 v[172:173], v[76:77], v[140:141], v[238:239]
	s_waitcnt vmcnt(5)
	v_pk_fma_f32 v[70:71], v[70:71], v[130:131], v[248:249]
	v_pk_fma_f32 v[68:69], v[68:69], v[128:129], v[246:247]
	v_pk_fma_f32 v[76:77], v[74:75], v[134:135], v[244:245]
	v_pk_fma_f32 v[72:73], v[72:73], v[132:133], v[242:243]
	s_waitcnt vmcnt(4)
	v_pk_fma_f32 v[64:65], v[64:65], v[136:137], v[250:251]
	v_mul_f32_e32 v74, v173, v173
	v_mul_f32_e32 v75, v79, v79
	v_mul_f32_e32 v180, v69, v69
	v_mul_f32_e32 v181, v71, v71
	v_pk_fma_f32 v[66:67], v[66:67], v[138:139], v[252:253]
	v_mul_f32_e32 v176, v73, v73
	v_mul_f32_e32 v182, v65, v65
	v_fmac_f32_e32 v74, v172, v172
	v_fmac_f32_e32 v75, v78, v78
	v_fmac_f32_e32 v180, v68, v68
	v_fmac_f32_e32 v181, v70, v70
	v_mul_f32_e32 v177, v77, v77
	v_mul_f32_e32 v183, v67, v67
	v_fmac_f32_e32 v176, v72, v72
	v_fmac_f32_e32 v182, v64, v64
	v_add_f32_e32 v74, v74, v75
	v_add_f32_e32 v75, v180, v181
	v_fmac_f32_e32 v177, v76, v76
	v_fmac_f32_e32 v183, v66, v66
	v_add_f32_e32 v74, v74, v176
	v_add_f32_e32 v75, v75, v182
	v_add_f32_e32 v74, v177, v74
	v_add_f32_e32 v75, v183, v75
	v_add_f32_e32 v74, v74, v75
	ds_bpermute_b32 v75, v165, v74
	s_waitcnt lgkmcnt(0)
	v_add_f32_e32 v74, v74, v75
	ds_bpermute_b32 v75, v197, v74
	s_and_saveexec_b64 s[2:3], s[0:1]
	s_cbranch_execz .LBB0_334
	s_waitcnt lgkmcnt(0)
	v_add_f32_e32 v74, v74, v75
	ds_write_b32 v188, v74 offset:192
.LBB0_334:
	s_or_b64 exec, exec, s[2:3]
	v_lshlrev_b64 v[176:177], 13, v[178:179]
	s_waitcnt lgkmcnt(0)
	v_lshl_add_u64 v[74:75], v[176:177], 0, s[20:21]
	v_lshl_add_u64 v[184:185], v[154:155], 0, v[74:75]
	v_lshl_add_u32 v250, s28, 8, v186
	v_or_b32_e32 v250, 0x90, v250
	v_mov_b32_e32 v251, 0
	v_lshlrev_b64 v[250:251], 13, v[250:251]
	v_lshl_add_u64 v[252:253], v[154:155], 0, v[250:251]
	global_load_dwordx4 v[238:241], v[252:253], off nt
	global_load_dwordx4 v[242:245], v[252:253], off offset:16 nt
	global_load_dwordx4 v[246:249], v[252:253], off offset:512 nt
	s_nop 0
	global_load_dwordx4 v[250:253], v[252:253], off offset:528 nt
	s_waitcnt vmcnt(7)
	v_pk_fma_f32 v[62:63], v[62:63], v[142:143], v[224:225]
	v_pk_fma_f32 v[60:61], v[60:61], v[140:141], v[222:223]
	s_waitcnt vmcnt(5)
	v_pk_fma_f32 v[54:55], v[54:55], v[130:131], v[232:233]
	v_pk_fma_f32 v[52:53], v[52:53], v[128:129], v[230:231]
	v_pk_fma_f32 v[56:57], v[56:57], v[132:133], v[226:227]
	s_waitcnt vmcnt(4)
	v_pk_fma_f32 v[48:49], v[48:49], v[136:137], v[234:235]
	v_mul_f32_e32 v180, v61, v61
	v_mul_f32_e32 v181, v63, v63
	v_mul_f32_e32 v184, v53, v53
	v_mul_f32_e32 v185, v55, v55
	v_pk_fma_f32 v[58:59], v[58:59], v[134:135], v[228:229]
	v_pk_fma_f32 v[50:51], v[50:51], v[138:139], v[236:237]
	v_mul_f32_e32 v182, v57, v57
	v_mul_f32_e32 v198, v49, v49
	v_fmac_f32_e32 v180, v60, v60
	v_fmac_f32_e32 v181, v62, v62
	v_fmac_f32_e32 v184, v52, v52
	v_fmac_f32_e32 v185, v54, v54
	v_mul_f32_e32 v183, v59, v59
	v_mul_f32_e32 v199, v51, v51
	v_fmac_f32_e32 v182, v56, v56
	v_fmac_f32_e32 v198, v48, v48
	v_add_f32_e32 v180, v180, v181
	v_add_f32_e32 v181, v184, v185
	v_fmac_f32_e32 v183, v58, v58
	v_fmac_f32_e32 v199, v50, v50
	v_add_f32_e32 v180, v180, v182
	v_add_f32_e32 v181, v181, v198
	v_add_f32_e32 v180, v183, v180
	v_add_f32_e32 v181, v199, v181
	v_add_f32_e32 v180, v180, v181
	ds_bpermute_b32 v181, v165, v180
	s_waitcnt lgkmcnt(0)
	v_add_f32_e32 v180, v180, v181
	ds_bpermute_b32 v181, v197, v180
	s_and_saveexec_b64 s[2:3], s[0:1]
	s_cbranch_execz .LBB0_336
	s_waitcnt lgkmcnt(0)
	v_add_f32_e32 v180, v180, v181
	ds_write_b32 v188, v180 offset:512
;     __device__ __forceinline__ void operator()(f32x4 (&acc)[2][2][4][2], const pg8::Unit& u, int wr, int wc, int fr, int fq) const {
;     ...
;         for (int ai = 0; ai < 2; ++ai)
; #pragma unroll
;             for (int m = 0; m < 4; ++m) {
;                 const size_t ro = (size_t)(row0 + ai * 128 + m * 16) * DM + col0;
;                 float s = 0.f;
; #pragma unroll
;                 for (int bj = 0; bj < 2; ++bj) {
;                     const f32x4 x0 = __builtin_nontemporal_load((const f32x4*)(x + ro + bj * 128)), x1 = __builtin_nontemporal_load((const f32x4*)(x + ro + bj * 128 + 4));
;                     const f32x4 h0 = x0 + gv[bj][0] * acc[ai][bj][m][0], h1 = x1 + gv[bj][1] * acc[ai][bj][m][1];
;                     acc[ai][bj][m][0] = h0; acc[ai][bj][m][1] = h1;
;                     s += (h0.x * h0.x + h0.y * h0.y) + (h0.z * h0.z + h0.w * h0.w) + (h1.x * h1.x + h1.y * h1.y) + (h1.z * h1.z + h1.w * h1.w);
;                 }
;                 s += __shfl_xor(s, 16); s += __shfl_xor(s, 32);
;                 if (fq == 0) sc[wc * 256 + ai * 128 + wr * 64 + m * 16 + fr] = s;
.LBB0_336:
	s_or_b64 exec, exec, s[2:3]
	v_lshl_add_u64 v[176:177], v[176:177], 0, s[22:23]
	v_lshl_add_u64 v[184:185], v[154:155], 0, v[176:177]
	s_waitcnt lgkmcnt(0)
	v_lshl_add_u32 v234, s28, 8, v186
	v_or_b32_e32 v234, 0xa0, v234
	v_mov_b32_e32 v235, 0
	v_lshlrev_b64 v[234:235], 13, v[234:235]
	v_lshl_add_u64 v[236:237], v[154:155], 0, v[234:235]
	global_load_dwordx4 v[222:225], v[236:237], off nt
	global_load_dwordx4 v[226:229], v[236:237], off offset:16 nt
	global_load_dwordx4 v[230:233], v[236:237], off offset:512 nt
	s_nop 0
	global_load_dwordx4 v[234:237], v[236:237], off offset:528 nt
	s_waitcnt vmcnt(7)
	v_pk_fma_f32 v[46:47], v[46:47], v[142:143], v[240:241]
	v_pk_fma_f32 v[44:45], v[44:45], v[140:141], v[238:239]
	s_waitcnt vmcnt(5)
	v_pk_fma_f32 v[38:39], v[38:39], v[130:131], v[248:249]
	v_pk_fma_f32 v[36:37], v[36:37], v[128:129], v[246:247]
	v_pk_fma_f32 v[40:41], v[40:41], v[132:133], v[242:243]
	s_waitcnt vmcnt(4)
	v_pk_fma_f32 v[32:33], v[32:33], v[136:137], v[250:251]
	v_mul_f32_e32 v180, v45, v45
	v_mul_f32_e32 v181, v47, v47
	v_mul_f32_e32 v184, v37, v37
	v_mul_f32_e32 v185, v39, v39
	v_pk_fma_f32 v[42:43], v[42:43], v[134:135], v[244:245]
	v_pk_fma_f32 v[34:35], v[34:35], v[138:139], v[252:253]
	v_mul_f32_e32 v182, v41, v41
	v_mul_f32_e32 v198, v33, v33
	v_fmac_f32_e32 v180, v44, v44
	v_fmac_f32_e32 v181, v46, v46
	v_fmac_f32_e32 v184, v36, v36
	v_fmac_f32_e32 v185, v38, v38
	v_mul_f32_e32 v183, v43, v43
	v_mul_f32_e32 v199, v35, v35
	v_fmac_f32_e32 v182, v40, v40
	v_fmac_f32_e32 v198, v32, v32
	v_add_f32_e32 v180, v180, v181
	v_add_f32_e32 v181, v184, v185
	v_fmac_f32_e32 v183, v42, v42
	v_fmac_f32_e32 v199, v34, v34
	v_add_f32_e32 v180, v180, v182
	v_add_f32_e32 v181, v181, v198
	v_add_f32_e32 v180, v183, v180
	v_add_f32_e32 v181, v199, v181
	v_add_f32_e32 v180, v180, v181
	ds_bpermute_b32 v181, v165, v180
	s_waitcnt lgkmcnt(0)
	v_add_f32_e32 v180, v180, v181
	ds_bpermute_b32 v181, v197, v180
	s_and_saveexec_b64 s[2:3], s[0:1]
	s_cbranch_execz .LBB0_338
	s_waitcnt lgkmcnt(0)
	v_add_f32_e32 v180, v180, v181
	ds_write_b32 v188, v180 offset:576
.LBB0_338:
	s_or_b64 exec, exec, s[2:3]
	s_waitcnt lgkmcnt(0)
	v_lshlrev_b64 v[180:181], 13, v[178:179]
	v_lshl_add_u64 v[178:179], v[180:181], 0, s[24:25]
	v_lshl_add_u64 v[198:199], v[154:155], 0, v[178:179]
	v_lshl_add_u32 v250, s28, 8, v186
	v_or_b32_e32 v250, 0xb0, v250
	v_mov_b32_e32 v251, 0
	v_lshlrev_b64 v[250:251], 13, v[250:251]
	v_lshl_add_u64 v[252:253], v[154:155], 0, v[250:251]
	global_load_dwordx4 v[238:241], v[252:253], off nt
	global_load_dwordx4 v[242:245], v[252:253], off offset:16 nt
	global_load_dwordx4 v[246:249], v[252:253], off offset:512 nt
	s_nop 0
	global_load_dwordx4 v[250:253], v[252:253], off offset:528 nt
	s_waitcnt vmcnt(7)
	v_pk_fma_f32 v[30:31], v[30:31], v[142:143], v[224:225]
	v_pk_fma_f32 v[28:29], v[28:29], v[140:141], v[222:223]
	s_waitcnt vmcnt(5)
	v_pk_fma_f32 v[22:23], v[22:23], v[130:131], v[232:233]
	v_pk_fma_f32 v[20:21], v[20:21], v[128:129], v[230:231]
	v_pk_fma_f32 v[24:25], v[24:25], v[132:133], v[226:227]
	s_waitcnt vmcnt(4)
	v_pk_fma_f32 v[16:17], v[16:17], v[136:137], v[234:235]
	v_mul_f32_e32 v182, v29, v29
	v_mul_f32_e32 v183, v31, v31
	v_mul_f32_e32 v198, v21, v21
	v_mul_f32_e32 v199, v23, v23
	v_pk_fma_f32 v[26:27], v[26:27], v[134:135], v[228:229]
	v_pk_fma_f32 v[18:19], v[18:19], v[138:139], v[236:237]
	v_mul_f32_e32 v184, v25, v25
	v_mul_f32_e32 v201, v17, v17
	v_fmac_f32_e32 v182, v28, v28
	v_fmac_f32_e32 v183, v30, v30
	v_fmac_f32_e32 v198, v20, v20
	v_fmac_f32_e32 v199, v22, v22
	v_mul_f32_e32 v185, v27, v27
	v_mul_f32_e32 v202, v19, v19
	v_fmac_f32_e32 v184, v24, v24
	v_fmac_f32_e32 v201, v16, v16
	v_add_f32_e32 v182, v182, v183
	v_add_f32_e32 v183, v198, v199
	v_fmac_f32_e32 v185, v26, v26
	v_fmac_f32_e32 v202, v18, v18
	v_add_f32_e32 v182, v182, v184
	v_add_f32_e32 v183, v183, v201
	v_add_f32_e32 v182, v185, v182
	v_add_f32_e32 v183, v202, v183
	v_add_f32_e32 v182, v182, v183
	ds_bpermute_b32 v183, v165, v182
	s_waitcnt lgkmcnt(0)
	v_add_f32_e32 v182, v182, v183
	ds_bpermute_b32 v183, v197, v182
	s_and_saveexec_b64 s[2:3], s[0:1]
	s_cbranch_execz .LBB0_340
	s_waitcnt lgkmcnt(0)
	v_add_f32_e32 v182, v182, v183
	ds_write_b32 v188, v182 offset:640
.LBB0_340:
	s_or_b64 exec, exec, s[2:3]
	v_lshl_add_u64 v[180:181], v[180:181], 0, s[26:27]
	s_waitcnt lgkmcnt(0)
	v_lshl_add_u64 v[182:183], v[154:155], 0, v[180:181]
	s_waitcnt vmcnt(3)
	v_pk_fma_f32 v[182:183], v[14:15], v[142:143], v[240:241]
	v_pk_fma_f32 v[184:185], v[12:13], v[140:141], v[238:239]
	s_waitcnt vmcnt(2)
	v_pk_fma_f32 v[140:141], v[10:11], v[134:135], v[244:245]
	v_pk_fma_f32 v[142:143], v[8:9], v[132:133], v[242:243]
	s_waitcnt vmcnt(1)
	v_pk_fma_f32 v[132:133], v[6:7], v[130:131], v[248:249]
	v_pk_fma_f32 v[134:135], v[4:5], v[128:129], v[246:247]
	s_waitcnt vmcnt(0)
	v_pk_fma_f32 v[130:131], v[0:1], v[136:137], v[250:251]
	v_mul_f32_e32 v0, v185, v185
	v_mul_f32_e32 v1, v183, v183
	v_mul_f32_e32 v4, v135, v135
	v_mul_f32_e32 v5, v133, v133
	v_pk_fma_f32 v[128:129], v[2:3], v[138:139], v[252:253]
	v_mul_f32_e32 v2, v143, v143
	v_mul_f32_e32 v6, v131, v131
	v_fmac_f32_e32 v0, v184, v184
	v_fmac_f32_e32 v1, v182, v182
	v_fmac_f32_e32 v4, v134, v134
	v_fmac_f32_e32 v5, v132, v132
	v_mul_f32_e32 v3, v141, v141
	v_mul_f32_e32 v7, v129, v129
	v_fmac_f32_e32 v2, v142, v142
	v_fmac_f32_e32 v6, v130, v130
	v_add_f32_e32 v0, v0, v1
	v_add_f32_e32 v1, v4, v5
	v_fmac_f32_e32 v3, v140, v140
	v_fmac_f32_e32 v7, v128, v128
	v_add_f32_e32 v0, v0, v2
	v_add_f32_e32 v1, v1, v6
	v_add_f32_e32 v0, v3, v0
	v_add_f32_e32 v1, v7, v1
	v_add_f32_e32 v0, v0, v1
	ds_bpermute_b32 v1, v165, v0
	s_waitcnt lgkmcnt(0)
	v_add_f32_e32 v0, v0, v1
	ds_bpermute_b32 v1, v197, v0
	s_and_saveexec_b64 s[2:3], s[0:1]
	s_cbranch_execz .LBB0_342
	s_waitcnt lgkmcnt(0)
	v_add_f32_e32 v0, v0, v1
	ds_write_b32 v188, v0 offset:704
